# P2 RG-LRU chunk-carry pass: loads of all (<=7) recurrence steps issued up front, recurrence applied in the same order
# speedup vs baseline: 1.0038x; 1.0002x over previous
; __global__ void __launch_bounds__(NTHR, LB2) hymba_fwd(Args a) {
;     ...
;       for (int L = P2B_FIRST; L < 256; L += P2B_STRIDE) { const int pm = L >> 3, nblk = L & 7, j = pm & 7, c8 = nblk * 128 + (tid & 15) * 8;
;         f32x4 hi0 = {0.f, 0.f, 0.f, 0.f}, hi1 = {0.f, 0.f, 0.f, 0.f};
;         for (int i = 0; i < j; ++i) { const float* eh = ENDH + (pm - j + i) * 1024 + c8; const float* ea = ENDA + (pm - j + i) * 1024 + c8;
;             hi0 = *(const f32x4*)ea * hi0 + *(const f32x4*)eh; hi1 = *(const f32x4*)(ea + 4) * hi1 + *(const f32x4*)(eh + 4); }
.LBB0_791:
	s_and_b64 vcc, exec, s[36:37]
	v_mov_b32_e32 v13, v5
	v_mov_b32_e32 v12, v5
	v_mov_b32_e32 v11, v5
	v_mov_b32_e32 v10, v5
	v_mov_b32_e32 v17, v5
	v_mov_b32_e32 v16, v5
	v_mov_b32_e32 v15, v5
	v_mov_b32_e32 v14, v5
	s_cbranch_vccnz .LBB0_794
	s_lshl_b32 s0, s6, 13
	v_mov_b32_e32 v10, 0
	s_waitcnt lgkmcnt(0)
	v_lshl_add_u64 v[0:1], s[0:1], 2, v[8:9]
	s_mov_b64 s[12:13], 0
	v_mov_b32_e32 v11, v10
	v_mov_b32_e32 v12, v10
	v_mov_b32_e32 v13, v10
	v_mov_b32_e32 v14, v10
	v_mov_b32_e32 v15, v10
	v_mov_b32_e32 v16, v10
	v_mov_b32_e32 v17, v10
	s_cmp_eq_u32 s4, 0x0
	s_cbranch_scc1 .Llruc_issued
	v_lshl_add_u64 v[2:3], v[0:1], 0, s[12:13]
	s_mov_b64 s[16:17], 0x15b00000
	v_lshl_add_u64 v[26:27], v[2:3], 0, s[16:17]
	s_mov_b64 s[16:17], 0x15b40000
	v_lshl_add_u64 v[18:19], v[2:3], 0, s[16:17]
	global_load_dwordx4 v[128:131], v[18:19], off offset:16
	global_load_dwordx4 v[132:135], v[26:27], off offset:16
	global_load_dwordx4 v[136:139], v[18:19], off
	global_load_dwordx4 v[140:143], v[26:27], off
	s_add_u32 s12, s12, 0x1000
	s_addc_u32 s13, s13, 0
	s_cmp_eq_u32 s4, 0x1000
	s_cbranch_scc1 .Llruc_issued
	v_lshl_add_u64 v[2:3], v[0:1], 0, s[12:13]
	s_mov_b64 s[16:17], 0x15b00000
	v_lshl_add_u64 v[26:27], v[2:3], 0, s[16:17]
	s_mov_b64 s[16:17], 0x15b40000
	v_lshl_add_u64 v[18:19], v[2:3], 0, s[16:17]
	global_load_dwordx4 v[144:147], v[18:19], off offset:16
	global_load_dwordx4 v[148:151], v[26:27], off offset:16
	global_load_dwordx4 v[152:155], v[18:19], off
	global_load_dwordx4 v[156:159], v[26:27], off
	s_add_u32 s12, s12, 0x1000
	s_addc_u32 s13, s13, 0
	s_cmp_eq_u32 s4, 0x2000
	s_cbranch_scc1 .Llruc_issued
	v_lshl_add_u64 v[2:3], v[0:1], 0, s[12:13]
	s_mov_b64 s[16:17], 0x15b00000
	v_lshl_add_u64 v[26:27], v[2:3], 0, s[16:17]
	s_mov_b64 s[16:17], 0x15b40000
	v_lshl_add_u64 v[18:19], v[2:3], 0, s[16:17]
	global_load_dwordx4 v[160:163], v[18:19], off offset:16
	global_load_dwordx4 v[164:167], v[26:27], off offset:16
	global_load_dwordx4 v[168:171], v[18:19], off
	global_load_dwordx4 v[172:175], v[26:27], off
	s_add_u32 s12, s12, 0x1000
	s_addc_u32 s13, s13, 0
	s_cmp_eq_u32 s4, 0x3000
	s_cbranch_scc1 .Llruc_issued
	v_lshl_add_u64 v[2:3], v[0:1], 0, s[12:13]
	s_mov_b64 s[16:17], 0x15b00000
	v_lshl_add_u64 v[26:27], v[2:3], 0, s[16:17]
	s_mov_b64 s[16:17], 0x15b40000
	v_lshl_add_u64 v[18:19], v[2:3], 0, s[16:17]
	global_load_dwordx4 v[176:179], v[18:19], off offset:16
	global_load_dwordx4 v[180:183], v[26:27], off offset:16
	global_load_dwordx4 v[184:187], v[18:19], off
	global_load_dwordx4 v[188:191], v[26:27], off
	s_add_u32 s12, s12, 0x1000
	s_addc_u32 s13, s13, 0
	s_cmp_eq_u32 s4, 0x4000
	s_cbranch_scc1 .Llruc_issued
	v_lshl_add_u64 v[2:3], v[0:1], 0, s[12:13]
	s_mov_b64 s[16:17], 0x15b00000
	v_lshl_add_u64 v[26:27], v[2:3], 0, s[16:17]
	s_mov_b64 s[16:17], 0x15b40000
	v_lshl_add_u64 v[18:19], v[2:3], 0, s[16:17]
	global_load_dwordx4 v[192:195], v[18:19], off offset:16
	global_load_dwordx4 v[196:199], v[26:27], off offset:16
	global_load_dwordx4 v[200:203], v[18:19], off
	global_load_dwordx4 v[204:207], v[26:27], off
	s_add_u32 s12, s12, 0x1000
	s_addc_u32 s13, s13, 0
	s_cmp_eq_u32 s4, 0x5000
	s_cbranch_scc1 .Llruc_issued
	v_lshl_add_u64 v[2:3], v[0:1], 0, s[12:13]
	s_mov_b64 s[16:17], 0x15b00000
	v_lshl_add_u64 v[26:27], v[2:3], 0, s[16:17]
	s_mov_b64 s[16:17], 0x15b40000
	v_lshl_add_u64 v[18:19], v[2:3], 0, s[16:17]
	global_load_dwordx4 v[208:211], v[18:19], off offset:16
	global_load_dwordx4 v[212:215], v[26:27], off offset:16
	global_load_dwordx4 v[216:219], v[18:19], off
	global_load_dwordx4 v[220:223], v[26:27], off
	s_add_u32 s12, s12, 0x1000
	s_addc_u32 s13, s13, 0
	s_cmp_eq_u32 s4, 0x6000
	s_cbranch_scc1 .Llruc_issued
	v_lshl_add_u64 v[2:3], v[0:1], 0, s[12:13]
	s_mov_b64 s[16:17], 0x15b00000
	v_lshl_add_u64 v[26:27], v[2:3], 0, s[16:17]
	s_mov_b64 s[16:17], 0x15b40000
	v_lshl_add_u64 v[18:19], v[2:3], 0, s[16:17]
	global_load_dwordx4 v[224:227], v[18:19], off offset:16
	global_load_dwordx4 v[228:231], v[26:27], off offset:16
	global_load_dwordx4 v[232:235], v[18:19], off
	global_load_dwordx4 v[236:239], v[26:27], off
	s_add_u32 s12, s12, 0x1000
	s_addc_u32 s13, s13, 0
.Llruc_issued:
	s_waitcnt vmcnt(0)
	s_cmp_eq_u32 s4, 0x0
	s_cbranch_scc1 .Llruc_done
	v_pk_fma_f32 v[16:17], v[16:17], v[130:131], v[134:135]
	v_pk_fma_f32 v[14:15], v[14:15], v[128:129], v[132:133]
	v_pk_fma_f32 v[12:13], v[12:13], v[138:139], v[142:143]
	v_pk_fma_f32 v[10:11], v[10:11], v[136:137], v[140:141]
	s_cmp_eq_u32 s4, 0x1000
	s_cbranch_scc1 .Llruc_done
	v_pk_fma_f32 v[16:17], v[16:17], v[146:147], v[150:151]
	v_pk_fma_f32 v[14:15], v[14:15], v[144:145], v[148:149]
	v_pk_fma_f32 v[12:13], v[12:13], v[154:155], v[158:159]
	v_pk_fma_f32 v[10:11], v[10:11], v[152:153], v[156:157]
	s_cmp_eq_u32 s4, 0x2000
	s_cbranch_scc1 .Llruc_done
	v_pk_fma_f32 v[16:17], v[16:17], v[162:163], v[166:167]
	v_pk_fma_f32 v[14:15], v[14:15], v[160:161], v[164:165]
	v_pk_fma_f32 v[12:13], v[12:13], v[170:171], v[174:175]
	v_pk_fma_f32 v[10:11], v[10:11], v[168:169], v[172:173]
	s_cmp_eq_u32 s4, 0x3000
	s_cbranch_scc1 .Llruc_done
	v_pk_fma_f32 v[16:17], v[16:17], v[178:179], v[182:183]
	v_pk_fma_f32 v[14:15], v[14:15], v[176:177], v[180:181]
	v_pk_fma_f32 v[12:13], v[12:13], v[186:187], v[190:191]
	v_pk_fma_f32 v[10:11], v[10:11], v[184:185], v[188:189]
	s_cmp_eq_u32 s4, 0x4000
	s_cbranch_scc1 .Llruc_done
	v_pk_fma_f32 v[16:17], v[16:17], v[194:195], v[198:199]
	v_pk_fma_f32 v[14:15], v[14:15], v[192:193], v[196:197]
	v_pk_fma_f32 v[12:13], v[12:13], v[202:203], v[206:207]
	v_pk_fma_f32 v[10:11], v[10:11], v[200:201], v[204:205]
	s_cmp_eq_u32 s4, 0x5000
	s_cbranch_scc1 .Llruc_done
	v_pk_fma_f32 v[16:17], v[16:17], v[210:211], v[214:215]
	v_pk_fma_f32 v[14:15], v[14:15], v[208:209], v[212:213]
	v_pk_fma_f32 v[12:13], v[12:13], v[218:219], v[222:223]
	v_pk_fma_f32 v[10:11], v[10:11], v[216:217], v[220:221]
	s_cmp_eq_u32 s4, 0x6000
	s_cbranch_scc1 .Llruc_done
	v_pk_fma_f32 v[16:17], v[16:17], v[226:227], v[230:231]
	v_pk_fma_f32 v[14:15], v[14:15], v[224:225], v[228:229]
	v_pk_fma_f32 v[12:13], v[12:13], v[234:235], v[238:239]
	v_pk_fma_f32 v[10:11], v[10:11], v[232:233], v[236:237]
.Llruc_done:
.LBB0_794:
	s_mov_b32 s0, 0
	v_mov_b32_e32 v26, v24
	v_mov_b32_e32 v18, v23
	s_branch .LBB0_796
